# DONE hand-off as L2-resident per-quarter byte flags when all quarter-workgroups share an XCD (counter + atomics otherwise)
# baseline (speedup 1.0000x reference)
; #define RD_PREFETCH_A(cc) do { const int soA_ = (b * SEQ + 16 * (cc)) * 256; \
;                 _Pragma("unroll") for (int ks = 0; ks < 3; ++ks) { nAW[ks] = __builtin_bit_cast(bf16x8, __builtin_amdgcn_raw_buffer_load_b128(rsWS, voA + 64 * ks, (int)WS_AW + soA_, 0)); nAA[ks] = __builtin_bit_cast(bf16x8, __builtin_amdgcn_raw_buffer_load_b128(rsWS, voA + 64 * ks, (int)WS_AA + soA_, 0)); } } while (0)
; __device__ void phase_rwkv_dist(const Params& p, LAS unsigned char* lds, int wg, int nwg) {
;     ...
;             { const int c0 = 6 * qw + pw; if (c0 < RC_NCHK) { RD_PREFETCH_A(c0); } }
.LBB0_648:
	s_and_b32 s91, s51, 7
	s_lshl_b32 s91, s91, 2
	s_add_i32 s91, s91, 0x90000
	v_mov_b32_e32 v182, s91
	global_load_dword v182, v182, s[96:97] sc1
	s_waitcnt vmcnt(0)
	v_readfirstlane_b32 s91, v182
	s_add_i32 s84, s91, -1
	s_and_b32 s84, s84, s91
	s_cmp_eq_u32 s84, 0
	s_cselect_b32 s91, 1, 0
	s_mov_b32 s32, 0x1010101
	s_cmp_eq_u32 s91, 0
	s_cselect_b32 s32, s49, s32
	v_mov_b32_e32 v252, 0
	s_mov_b32 s90, -1
	v_mov_b64_e32 v[42:43], v[6:7]
	v_mov_b64_e32 v[46:47], v[10:11]
	v_mov_b64_e32 v[50:51], v[14:15]
	v_mov_b64_e32 v[30:31], v[18:19]
	v_mov_b64_e32 v[34:35], v[22:23]
	v_mov_b64_e32 v[38:39], v[26:27]
	s_andn2_b64 vcc, exec, s[2:3]
	v_mov_b64_e32 v[40:41], v[4:5]
	v_mov_b64_e32 v[44:45], v[8:9]
	v_mov_b64_e32 v[48:49], v[12:13]
	v_mov_b64_e32 v[28:29], v[16:17]
	v_mov_b64_e32 v[32:33], v[20:21]
	v_mov_b64_e32 v[36:37], v[24:25]
	s_cbranch_vccnz .LBB0_650
	s_lshl_b32 s1, s16, 12
	s_lshl_b32 s17, s0, 21
	s_add_i32 s1, s17, s1
	s_add_i32 s2, s1, 0x100000
	s_add_i32 s1, s1, 0x500000
	buffer_load_dwordx4 v[28:31], v190, s[52:55], s2 offen
	buffer_load_dwordx4 v[40:43], v190, s[52:55], s1 offen
	buffer_load_dwordx4 v[32:35], v205, s[52:55], s2 offen
	buffer_load_dwordx4 v[44:47], v205, s[52:55], s1 offen
	buffer_load_dwordx4 v[36:39], v206, s[52:55], s2 offen
	buffer_load_dwordx4 v[48:51], v206, s[52:55], s1 offen
	s_lshl_b32 s85, s94, 20
	s_lshl_b32 s84, s16, 11
	s_add_i32 s85, s85, s84
	s_add_i32 s88, s85, 0xffffff80
	s_cmp_gt_i32 s85, 0
	s_cselect_b32 s88, s88, 0
	s_cselect_b32 s89, 0, 0xffffff80
	v_add_u32_e32 v178, s89, v191
	v_add_u32_e32 v179, s89, v207
	v_add_u32_e32 v180, s89, v208
	v_add_u32_e32 v181, s89, v209
	s_add_i32 s86, s85, 0x13800000
	s_add_i32 s87, s85, 0x17800000
	s_add_i32 s89, s88, 0x17800000
	s_add_i32 s88, s88, 0x13800000
	buffer_load_dwordx2 v[220:221], v191, s[52:55], s86 offen
	buffer_load_dwordx2 v[222:223], v207, s[52:55], s86 offen
	buffer_load_dwordx2 v[224:225], v207, s[52:55], s87 offen
	buffer_load_dwordx2 v[226:227], v191, s[52:55], s87 offen
	buffer_load_dwordx2 v[228:229], v178, s[52:55], s88 offen
	buffer_load_dwordx2 v[230:231], v179, s[52:55], s88 offen
	buffer_load_dwordx2 v[232:233], v179, s[52:55], s89 offen
	buffer_load_dwordx2 v[234:235], v178, s[52:55], s89 offen
	buffer_load_dwordx2 v[236:237], v208, s[52:55], s86 offen
	buffer_load_dwordx2 v[238:239], v209, s[52:55], s86 offen
	buffer_load_dwordx2 v[240:241], v209, s[52:55], s87 offen
	buffer_load_dwordx2 v[242:243], v208, s[52:55], s87 offen
	buffer_load_dwordx2 v[244:245], v180, s[52:55], s88 offen
	buffer_load_dwordx2 v[246:247], v181, s[52:55], s88 offen
	buffer_load_dwordx2 v[248:249], v181, s[52:55], s89 offen
	buffer_load_dwordx2 v[250:251], v180, s[52:55], s89 offen

; __device__ void phase_rwkv_dist(const Params& p, LAS unsigned char* lds, int wg, int nwg) {
;     ...
;                 if (ci >= RD_NG) { unsigned sp = 0; while (!dead && __hip_atomic_load(DONE + bh * 512 + (ci - RD_NG), __ATOMIC_RELAXED, __HIP_MEMORY_SCOPE_AGENT) < 256u) { __builtin_amdgcn_s_sleep(2); if (++sp > RD_SPIN_MAX) { if (lane == 0) atomicAdd(ERR, 1u); dead = true; } } }
.Lprep_nopend:
	v_readfirstlane_b32 s81, v252
	s_cmp_ge_u32 s81, s32
	s_cselect_b64 s[92:93], -1, 0
	v_mov_b64_e32 v[60:61], v[220:221]
	v_mov_b64_e32 v[62:63], v[222:223]
	v_mov_b64_e32 v[112:113], v[224:225]
	v_mov_b64_e32 v[94:95], v[226:227]
	v_mov_b64_e32 v[64:65], v[228:229]
	v_mov_b64_e32 v[66:67], v[230:231]
	v_mov_b64_e32 v[114:115], v[232:233]
	v_mov_b64_e32 v[96:97], v[234:235]
	v_mov_b64_e32 v[118:119], v[236:237]
	v_mov_b64_e32 v[104:105], v[238:239]
	v_mov_b64_e32 v[100:101], v[240:241]
	v_mov_b64_e32 v[108:109], v[242:243]
	v_mov_b64_e32 v[120:121], v[244:245]
	v_mov_b64_e32 v[106:107], v[246:247]
	v_mov_b64_e32 v[102:103], v[248:249]
	v_mov_b64_e32 v[110:111], v[250:251]
	s_cmpk_gt_i32 s2, 0x1ff
	s_cbranch_scc1 .LBB0_656
	s_lshl_b32 s85, s2, 11
	s_add_i32 s85, s85, s18
	s_cmp_lt_i32 s2, 56
	s_cbranch_scc1 .Lprep_nopoll
	s_lshl_b32 s86, s2, 2
	s_add_u32 s86, s19, s86
	s_addc_u32 s87, s40, 0
	s_cmp_eq_u32 s91, 0
	s_cbranch_scc1 .Lpk0_a
	global_load_dword v252, v1, s[86:87] offset:-224 sc1
	s_branch .Lpk0_j
.Lpk0_a:
	s_mov_b64 s[82:83], exec
	s_mov_b64 exec, 1
	global_atomic_add v252, v1, v1, s[86:87] offset:-224 sc0
	s_mov_b64 exec, s[82:83]
.Lpk0_j:
.Lprep_nopoll:
	s_add_i32 s86, s85, 0x13800000
	s_add_i32 s87, s85, 0x17800000
	s_add_i32 s88, s85, 0x137fff80
	s_add_i32 s89, s85, 0x177fff80
	buffer_load_dwordx2 v[220:221], v191, s[52:55], s86 offen
	buffer_load_dwordx2 v[222:223], v207, s[52:55], s86 offen
	buffer_load_dwordx2 v[224:225], v207, s[52:55], s87 offen
	buffer_load_dwordx2 v[226:227], v191, s[52:55], s87 offen
	buffer_load_dwordx2 v[228:229], v191, s[52:55], s88 offen
	buffer_load_dwordx2 v[230:231], v207, s[52:55], s88 offen
	buffer_load_dwordx2 v[232:233], v207, s[52:55], s89 offen
	buffer_load_dwordx2 v[234:235], v191, s[52:55], s89 offen
	buffer_load_dwordx2 v[236:237], v208, s[52:55], s86 offen
	buffer_load_dwordx2 v[238:239], v209, s[52:55], s86 offen
	buffer_load_dwordx2 v[240:241], v209, s[52:55], s87 offen
	buffer_load_dwordx2 v[242:243], v208, s[52:55], s87 offen
	buffer_load_dwordx2 v[244:245], v208, s[52:55], s88 offen
	buffer_load_dwordx2 v[246:247], v209, s[52:55], s88 offen
	buffer_load_dwordx2 v[248:249], v209, s[52:55], s89 offen
	buffer_load_dwordx2 v[250:251], v208, s[52:55], s89 offen
	s_lshl_b32 s2, s2, 12
	s_add_i32 s2, s2, s17
	s_add_i32 s3, s2, 0x100000
	s_add_i32 s2, s2, 0x500000
	buffer_load_dwordx4 v[28:31], v190, s[52:55], s3 offen
	buffer_load_dwordx4 v[40:43], v190, s[52:55], s2 offen
	buffer_load_dwordx4 v[32:35], v205, s[52:55], s3 offen
	buffer_load_dwordx4 v[44:47], v205, s[52:55], s2 offen
	buffer_load_dwordx4 v[36:39], v206, s[52:55], s3 offen
	buffer_load_dwordx4 v[48:51], v206, s[52:55], s2 offen

; __device__ void phase_rwkv_dist(const Params& p, LAS unsigned char* lds, int wg, int nwg) {
;     ...
;                 if (ci >= RD_NG) { unsigned sp = 0; while (!dead && __hip_atomic_load(DONE + bh * 512 + (ci - RD_NG), __ATOMIC_RELAXED, __HIP_MEMORY_SCOPE_AGENT) < 256u) { __builtin_amdgcn_s_sleep(2); if (++sp > RD_SPIN_MAX) { if (lane == 0) atomicAdd(ERR, 1u); dead = true; } } }
.LBB0_660:
	s_cmp_eq_u32 s91, 0
	s_cbranch_scc1 .Lpk1_a
	global_load_dword v101, v1, s[2:3] offset:-224 sc1
	s_branch .Lpk1_j

; __device__ void phase_rwkv_dist(const Params& p, LAS unsigned char* lds, int wg, int nwg) {
;     ...
;                 if (ci >= RD_NG) { unsigned sp = 0; while (!dead && __hip_atomic_load(DONE + bh * 512 + (ci - RD_NG), __ATOMIC_RELAXED, __HIP_MEMORY_SCOPE_AGENT) < 256u) { __builtin_amdgcn_s_sleep(2); if (++sp > RD_SPIN_MAX) { if (lane == 0) atomicAdd(ERR, 1u); dead = true; } } }
.Lpk1_j:
	s_movk_i32 s0, 0xff
	s_waitcnt vmcnt(0)
	v_readfirstlane_b32 s81, v101
	s_cmp_ge_u32 s81, s32
	s_cbranch_scc1 .LBB0_659
	s_sleep 2
	s_cmp_eq_u32 s91, 0
	s_cbranch_scc1 .Lpk2_a
	global_load_dword v101, v1, s[2:3] offset:-224 sc1
	s_branch .Lpk2_j

; __device__ void phase_rwkv_dist(const Params& p, LAS unsigned char* lds, int wg, int nwg) {
;     ...
;                 if (ci >= RD_NG) { unsigned sp = 0; while (!dead && __hip_atomic_load(DONE + bh * 512 + (ci - RD_NG), __ATOMIC_RELAXED, __HIP_MEMORY_SCOPE_AGENT) < 256u) { __builtin_amdgcn_s_sleep(2); if (++sp > RD_SPIN_MAX) { if (lane == 0) atomicAdd(ERR, 1u); dead = true; } } }
.Lpk2_j:
	s_waitcnt vmcnt(0)
	v_readfirstlane_b32 s81, v101
	s_cmp_ge_u32 s81, s32
	s_cbranch_scc1 .LBB0_659
	s_sleep 2
	s_cmp_eq_u32 s91, 0
	s_cbranch_scc1 .Lpk3_a
	global_load_dword v101, v1, s[2:3] offset:-224 sc1
	s_branch .Lpk3_j

; __device__ void phase_rwkv_dist(const Params& p, LAS unsigned char* lds, int wg, int nwg) {
;     ...
;                 if (ci >= RD_NG) { unsigned sp = 0; while (!dead && __hip_atomic_load(DONE + bh * 512 + (ci - RD_NG), __ATOMIC_RELAXED, __HIP_MEMORY_SCOPE_AGENT) < 256u) { __builtin_amdgcn_s_sleep(2); if (++sp > RD_SPIN_MAX) { if (lane == 0) atomicAdd(ERR, 1u); dead = true; } } }
.Lpk3_j:
	s_waitcnt vmcnt(0)
	v_readfirstlane_b32 s81, v101
	s_cmp_ge_u32 s81, s32
	s_cbranch_scc1 .LBB0_659
	s_cmp_gt_u32 s44, 0x7fffd
	s_cselect_b64 s[0:1], -1, 0
	s_and_b64 s[6:7], s[4:5], s[0:1]
	s_sleep 2
	s_and_saveexec_b64 s[0:1], s[6:7]
	s_cbranch_execz .LBB0_666
	s_mov_b64 s[6:7], exec
	v_mbcnt_lo_u32_b32 v101, s6, 0
	v_mbcnt_hi_u32_b32 v101, s7, v101
	v_cmp_eq_u32_e32 vcc, 0, v101
	s_and_b64 s[46:47], exec, vcc
	s_mov_b64 exec, s[46:47]
	s_cbranch_execz .LBB0_666
	s_bcnt1_i32_b64 s6, s[6:7]
	v_mov_b32_e32 v101, s6
	global_atomic_add v1, v101, s[96:97]

; #define LAS __attribute__((address_space(3)))
; #define RD_PEEK(cc) __hip_atomic_load(READY + bh * 512 + (cc), __ATOMIC_RELAXED, __HIP_MEMORY_SCOPE_AGENT)
; __device__ void phase_rwkv_dist(const Params& p, LAS unsigned char* lds, int wg, int nwg) {
;     ...
;             const int fw = wave - 4;
;             __builtin_amdgcn_s_setprio(2);
;             const int voV = (r * 64 + 16 * qw + 4 * q) * 2;
;             const f32x4 muv = *(LAS const f32x4*)(cst + 7 * 64 + 16 * qw + 4 * q);
;             u32x4 fa[2][10]; u32x4 fg[2]; u32x2 fv[2][2];
;     ...
;             bf16_t* SS = (bf16_t*)p.out; const float* CD = (const float*)(p.ws + WS_CTL + WS_CD);
;             const int nitem = (BATCH * 32 * 64 * 32 + nwg * 64 - 1) / (nwg * 64), nstep = ((nitem + 3) / 4) * 128;
;             const int per = (nitem + 3) / 4;
;             int s2 = (unit == wg) ? 0 : nstep; f32x4 hh = zero4;
;             RD_ISSUE(fw, 0, 0u);
;             for (int c2 = fw; c2 < RC_NCHK; c2 += 8) {
;                 const unsigned pr1 = RD_PEEK(c2 + 4), pr0 = (c2 + 8 < RC_NCHK) ? RD_PEEK(c2 + 8) : 0u;
;                 u32x2 raw[4]; float dd[4]; bf16_t* qq[4]; bool ok[4];
; #pragma unroll
;                 for (int k = 0; k < 4; ++k) { const int ss = s2 + k, item = fw * per + (ss >> 7), cc = ss & 127, idx = item * (nwg * 64) + wg * 64 + lane; ok[k] = ss < nstep && (ss >> 7) < per && item < nitem && idx < BATCH * 32 * 64 * 32;
;                     const int n4 = idx & 31, pp = (idx >> 5) & 63, eg = (idx >> 11) & 31, bb = idx >> 16;
;                     qq[k] = SS + ((((size_t)bb * 128 + cc) * 32 + eg) * 64 + pp) * 128 + 4 * n4; raw[k] = (u32x2){0u, 0u}; dd[k] = 0.f;
;                     if (ok[k]) { raw[k] = *(const u32x2*)qq[k]; dd[k] = CD[(bb * 128 + cc) * 32 + eg]; } }
.LBB0_681:
	v_readlane_b32 s6, v253, 51
	s_cmp_lg_u32 s51, s6
	v_readlane_b32 s6, v254, 18
	v_readlane_b32 s7, v254, 19
	s_cselect_b32 s81, s56, 0
	s_andn2_b64 vcc, exec, s[6:7]
	s_cbranch_vccnz .LBB0_769
	s_and_b32 s100, s51, 7
	s_lshl_b32 s100, s100, 2
	s_add_i32 s100, s100, 0x90000
	v_mov_b32_e32 v251, s100
	global_load_dword v251, v251, s[96:97] sc1
	v_mov_b32_e32 v250, s72
	v_mov_b32_e32 v249, 1
	s_waitcnt vmcnt(0)
	v_readfirstlane_b32 s100, v251
	s_add_i32 s101, s100, -1
	s_and_b32 s101, s101, s100
	s_cmp_eq_u32 s101, 0
	s_cselect_b32 s100, 1, 0
	v_mov_b32_e32 v251, s100
	v_writelane_b32 v254, s72, 46
	s_lshl_b32 s84, s94, 20
	v_readlane_b32 s6, v254, 14
	s_add_i32 s6, s80, s6
	s_add_i32 s7, s6, 0x2000
	buffer_load_dwordx4 v[80:83], v197, s[52:55], s7 offen sc1
	buffer_load_dwordx4 v[72:75], v196, s[52:55], s7 offen sc1
	s_add_i32 s7, s6, 0x1000
	buffer_load_dwordx4 v[88:91], v215, s[52:55], s7 offen sc1
	buffer_load_dwordx4 v[84:87], v213, s[52:55], s7 offen sc1
	buffer_load_dwordx4 v[96:99], v197, s[52:55], s7 offen sc1
	buffer_load_dwordx4 v[92:95], v196, s[52:55], s7 offen sc1
	buffer_load_dwordx4 v[64:67], v215, s[52:55], s6 offen sc1
	buffer_load_dwordx4 v[60:63], v213, s[52:55], s6 offen sc1
	buffer_load_dwordx4 v[68:71], v197, s[52:55], s6 offen sc1
	buffer_load_dwordx4 v[76:79], v196, s[52:55], s6 offen sc1
	v_readlane_b32 s7, v254, 16
	s_add_i32 s7, s84, s7
	s_add_i32 s16, s7, 0xdffff80
	v_or_b32_e32 v0, s40, v200
	s_cmp_gt_i32 s7, 0
	v_lshlrev_b32_e32 v157, 1, v0
	s_cselect_b32 s17, 0, 0xffffff80
	v_add_u32_e32 v0, s17, v157
	s_cselect_b32 s16, s16, 0xe000000
	s_add_i32 s7, s7, 0xe000000
	s_addk_i32 s6, 0x2800
	buffer_load_dwordx2 v[176:177], v0, s[52:55], s16 offen
	buffer_load_dwordx2 v[178:179], v157, s[52:55], s7 offen
	buffer_load_dwordx4 v[100:103], v202, s[52:55], s6 offen sc1
	v_readlane_b32 s6, v254, 0
	s_add_u32 s85, s6, s2
	v_readlane_b32 s2, v254, 2
	v_mov_b32_e32 v2, v1
	v_mov_b32_e32 v3, v1
	s_addc_u32 s86, s2, s3
	v_mov_b32_e32 v0, v1
	v_mov_b64_e32 v[58:59], v[2:3]
	v_readlane_b32 s2, v254, 42
	s_mov_b32 s95, s45
	v_mov_b64_e32 v[56:57], v[0:1]
	s_mov_b32 s72, s2
	v_readlane_b32 s3, v254, 43
	s_lshl_b32 s100, s72, 11
	s_add_i32 s100, s100, s84
	s_add_i32 s101, s100, 0xe002000
	buffer_load_dwordx2 v[184:185], v157, s[52:55], s101 offen
	s_add_i32 s101, s100, 0xe001f80
	buffer_load_dwordx2 v[182:183], v157, s[52:55], s101 offen
	s_lshl_b32 s100, s72, 11
	s_add_i32 s100, s100, s84
	s_add_i32 s101, s100, 0xe004000
	buffer_load_dwordx2 v[234:235], v157, s[52:55], s101 offen
	s_add_i32 s101, s100, 0xe003f80
	buffer_load_dwordx2 v[232:233], v157, s[52:55], s101 offen
	s_add_i32 s101, s100, 0xe006000
	buffer_load_dwordx2 v[238:239], v157, s[52:55], s101 offen
	s_add_i32 s101, s100, 0xe005f80
	buffer_load_dwordx2 v[236:237], v157, s[52:55], s101 offen
	s_lshl_b32 s100, s72, 2
	s_add_u32 s100, s82, s100
	s_addc_u32 s101, s83, 0
	global_load_dword v229, v1, s[100:101] offset:16 sc1
	global_load_dword v230, v1, s[100:101] offset:32 sc1
	s_mov_b32 s99, 0
	s_mov_b32 s32, 0
	v_mov_b32_e32 v2, 0
	s_ashr_i32 s2, s81, 7
	v_readlane_b32 s3, v254, 40
	s_add_i32 s3, s2, s3
	s_mul_i32 s16, s3, s57
	s_add_i32 s16, s16, s33
	s_cmp_lt_i32 s2, s48
	s_cselect_b64 s[46:47], -1, 0
	s_cmp_lt_i32 s3, s20
	s_cselect_b64 s[60:61], -1, 0
	s_ashr_i32 s2, s16, 16
	s_ashr_i32 s3, s2, 31
	s_bfe_u32 s17, s16, 0x5000b
	s_lshl_b64 s[18:19], s[2:3], 12
	s_lshl_b32 s2, s2, 12
	s_or_b32 s88, s18, s17
	s_or_b32 s87, s2, s17
	s_cmp_lt_i32 s81, s56
	s_cselect_b64 s[2:3], -1, 0
	v_or_b32_e32 v0, s16, v165
	s_and_b64 s[2:3], s[2:3], s[46:47]
	v_cmp_gt_i32_e32 vcc, s55, v0
	s_and_b64 s[2:3], s[2:3], s[60:61]
	s_and_b64 s[58:59], s[2:3], vcc
	s_lshl_b32 s2, s81, 5
	v_lshlrev_b32_e32 v0, 3, v0
	s_and_b32 s16, s2, 0xf80
	v_and_b32_e32 v0, 0x3f00, v0
	s_or_b32 s18, s88, s16
	v_lshl_add_u64 v[104:105], v[154:155], 0, v[0:1]
	s_lshl_b64 s[2:3], s[18:19], 14
	v_lshl_add_u64 v[158:159], v[104:105], 0, s[2:3]
	v_mov_b32_e32 v162, 0
	v_mov_b32_e32 v163, 0
	s_and_saveexec_b64 s[2:3], s[58:59]
	s_cbranch_execz .Lssd2p_687
	s_add_i32 s32, s32, 2
	s_or_b32 s16, s87, s16
	s_ashr_i32 s17, s16, 31
	s_lshl_b64 s[16:17], s[16:17], 2
	v_readlane_b32 s62, v253, 54
	v_readlane_b32 s63, v253, 55
	s_add_u32 s16, s62, s16
	s_addc_u32 s17, s63, s17
	global_load_dwordx2 v[162:163], v[158:159], off
	global_load_dword v2, v1, s[16:17]

.Lfetch_nop0:
	s_mov_b32 s99, 0
	s_cmp_lt_u32 s72, 8
	s_cbranch_scc1 .Lfetch_nodone
	v_readfirstlane_b32 s100, v251
	s_cmp_eq_u32 s100, 0
	s_cbranch_scc1 .Lfetch_done_at
	global_store_byte v250, v249, s[40:41] offset:-32
	global_store_byte v250, v249, s[40:41] offset:-16
	s_branch .Lfetch_done_j
.Lfetch_done_at:
	s_mov_b64 s[100:101], exec
	v_mbcnt_lo_u32_b32 v231, s100, 0
	v_mbcnt_hi_u32_b32 v231, s101, v231
	v_cmp_eq_u32_e32 vcc, 0, v231
	s_and_saveexec_b64 s[100:101], vcc
	v_mov_b32_e32 v231, 64
	global_atomic_add v1, v231, s[40:41] offset:-32
	global_atomic_add v1, v231, s[40:41] offset:-16
	s_or_b64 exec, exec, s[100:101]
.Lfetch_done_j:
	s_add_i32 s98, s98, 2
	s_mov_b32 s99, 2
